# conversion of the weights first needed in the gate/branch phase moved from phase 1 into the idle time of the attention phase (queue of item pairs run through the phase-1 item code); barrier before the
# baseline (speedup 1.0000x reference)
; #define LAS __attribute__((address_space(3)))
; DEVI unsigned xb_add(unsigned* p, unsigned v) { return __hip_atomic_fetch_add(p, v, __ATOMIC_RELAXED, __HIP_MEMORY_SCOPE_AGENT); }
; DEVI unsigned xb_xcc_id() { return (unsigned)__builtin_amdgcn_s_getreg((3 << 11) | 20) & 0xFu; }
; DEVI XcdBarrier xcd_barrier_post(unsigned* bar, volatile LAS unsigned* st) {
;   XcdBarrier b; b.bar = bar; b.x = xb_xcc_id(); b.st = st;
;   if (threadIdx.x == 0) (void)xb_add(&bar[XB_XCNT(b.x)], 1u);
;   return b;
; }
; __global__ void __launch_bounds__(512, 2) fwd_mega(Params p, int ph_lo, int ph_hi, int coop) {
;   extern __shared__ __attribute__((aligned(16))) char lds[];
;   __shared__ uint4 xb_words;
;   __shared__ int nsa_cnt_s[4];
;   __shared__ float p4_stage[768];
;   XcdBarrier xb;
;   if (coop) {
;     if (threadIdx.x == 0) xb_words = make_uint4(0u, 0u, 0u, 0u);
;     __syncthreads();
;     xb = xcd_barrier_post((unsigned*)(p.ws + OFF_BAR), (volatile LAS unsigned*)&xb_words);
;   }
_Z8fwd_mega6Paramsiii:
	s_mov_b32 s100, 0
	s_mov_b32 s101, 0
	s_load_dwordx8 s[88:95], s[0:1], 0xc0
	v_writelane_b32 v244, s2, 0
	s_waitcnt lgkmcnt(0)
	s_cmp_lg_u32 s94, 0
	s_cselect_b64 s[2:3], -1, 0
	v_writelane_b32 v244, s2, 1
	s_cmp_eq_u32 s94, 0
	s_nop 0
	v_writelane_b32 v244, s3, 2
	s_cbranch_scc1 .LBB0_7
	v_and_b32_e32 v1, 0x3ff, v0
	v_cmp_eq_u32_e32 vcc, 0, v1
	s_and_saveexec_b64 s[2:3], vcc
	v_mov_b32_e32 v2, 0
	v_mov_b32_e32 v3, v2
	v_mov_b32_e32 v4, v2
	v_mov_b32_e32 v5, v2
	ds_write_b128 v2, v[2:5] offset:3072
	s_or_b64 exec, exec, s[2:3]
	s_add_u32 s2, s90, 0xf588000
	s_addc_u32 s3, s91, 0
	v_writelane_b32 v244, s2, 51
	s_waitcnt lgkmcnt(0)
	s_barrier
	v_writelane_b32 v244, s3, 52
	s_getreg_b32 s2, hwreg(HW_REG_XCC_ID, 0, 4)
	s_and_b32 s8, s2, 15
	s_and_saveexec_b64 s[2:3], vcc
	s_cbranch_execz .LBB0_6
	s_mov_b64 s[4:5], exec
	v_mbcnt_lo_u32_b32 v1, s4, 0
	v_mbcnt_hi_u32_b32 v1, s5, v1
	v_cmp_eq_u32_e32 vcc, 0, v1
	s_and_b64 s[6:7], exec, vcc
	s_mov_b64 exec, s[6:7]
	s_cbranch_execz .LBB0_6
	s_bcnt1_i32_b64 s4, s[4:5]
	s_lshl_b32 s6, s8, 8
	v_mov_b32_e32 v2, s4
	v_readlane_b32 s4, v244, 51
	v_mov_b32_e32 v1, s6
	v_readlane_b32 s5, v244, 52
	s_nop 4
	global_atomic_add v1, v2, s[4:5] offset:1024
	v_readlane_b32 s6, v244, 0
	s_and_b32 s6, s6, 7
	s_lshl_b32 s6, s6, 2
	s_add_i32 s6, s6, 0x3600
	s_lshl_b32 s7, 1, s8
	v_mov_b32_e32 v3, s7
	v_mov_b32_e32 v4, s6
	global_atomic_or v4, v3, s[4:5]

; DEVI int vhalf() { int t = threadIdx.x >> 8; t = __builtin_amdgcn_readfirstlane(t); return t; }
; DEVI void pull_extras(const Params& p, int l, char* lds, volatile int* nsa_cnt, int max_pulls) {
;   unsigned* q = (unsigned*)(p.ws + OFF_BAR) + 3500 + l;
;   for (int n = 0; n < max_pulls; ++n) {
;     __syncthreads();
;     if (threadIdx.x == 0) nsa_cnt[2] = (int)atomicAdd(q, 2u);
;     __syncthreads();
;     const int base = nsa_cnt[2];
;     if (base >= P3B_EXTRA) break;
;     int i = base + vhalf();
.LBB0_600:
	s_or_b64 exec, exec, s[50:51]
	v_readlane_b32 s0, v243, 13
	s_cmp_lt_u32 s0, 0x80
	s_cbranch_scc1 .Lcv_done
.Lcv_loop:
	s_waitcnt vmcnt(0) lgkmcnt(0)
	s_barrier
	v_readlane_b32 s20, v242, 37
	v_readlane_b32 s21, v242, 38
	s_and_saveexec_b64 s[36:37], s[20:21]
	s_cbranch_execz .Lcv_bcast
	v_readlane_b32 s28, v244, 51
	v_readlane_b32 s29, v244, 52
	v_readlane_b32 s38, v242, 43
	s_lshl_b32 s38, s38, 5
	s_add_i32 s38, s38, 0x3680
	v_mov_b32_e32 v2, s38
	v_mov_b32_e32 v3, 2
	s_nop 3
	global_atomic_add v3, v2, v3, s[28:29] sc0
	s_waitcnt vmcnt(0)
	v_mov_b32_e32 v2, 0xc1c
	ds_write_b32 v2, v3
.Lcv_bcast:
	s_or_b64 exec, exec, s[36:37]
	s_waitcnt lgkmcnt(0)
	s_barrier
	v_mov_b32_e32 v2, 0xc1c
	ds_read_b32 v2, v2
	s_waitcnt lgkmcnt(0)
	v_readfirstlane_b32 s23, v2
	s_cmpk_ge_u32 s23, 0xe00
	s_cbranch_scc1 .Lcv_done
	v_readfirstlane_b32 s0, v220
	s_lshr_b32 s0, s0, 8
	s_add_i32 s23, s23, s0
	s_addk_i32 s23, 0x300
	s_add_i32 s20, s23, 1
	s_mov_b32 s101, 0x5a5a
	s_mov_b64 s[0:1], 0
	s_branch .Lp1_entry
.Lcv_ret:
	s_mov_b32 s101, 0
	s_branch .Lcv_loop
.Lcv_done:
	s_mov_b32 s101, 0
	s_mov_b64 s[0:1], 0

; DEVI int vblk() { return (int)blockIdx.x * 2 + vhalf(); }
; DEVI int vgrid() { return (int)gridDim.x * 2; }
; DEVI void phase1(const Params& p, int l, char* lds) {
;   char* ws = p.ws;
;   const float* xin = (l == 0) ? p.in[0] : p.out;
;   const int n_items = P1_CVT + P1_BIAS + (l == 0 ? P1_RMS : 0);
;   for (int item = vblk(); item < n_items; item += vgrid()) {
;     int i = item;
;     if (i < P1_CVT) {
.Lp1_entry:
	s_and_b64 s[0:1], s[0:1], exec
	v_readlane_b32 s40, v244, 3
	v_readlane_b32 s0, v242, 43
	v_readlane_b32 s41, v244, 4
	v_readlane_b32 s48, v244, 11
	v_readlane_b32 s49, v244, 12
	v_readlane_b32 s50, v244, 13
	v_readlane_b32 s51, v244, 14
	v_readlane_b32 s52, v244, 15
	v_readlane_b32 s53, v244, 16
	v_readlane_b32 s54, v244, 17
	v_readlane_b32 s55, v244, 18
	s_mov_b32 s28, s0
	s_cselect_b32 s5, s41, s89
	s_cselect_b32 s4, s40, s88
	v_readlane_b32 s1, v242, 44
	s_ashr_i32 s29, s0, 31
	s_lshl_b32 s36, s28, 10
	v_readlane_b32 s48, v244, 35
	s_lshl_b32 s25, s0, 1
	s_lshl_b64 s[0:1], s[28:29], 24
	s_ashr_i32 s37, s36, 31
	s_lshl_b64 s[38:39], s[28:29], 22
	s_waitcnt lgkmcnt(0)
	s_lshl_b32 s27, s28, 2
	v_readlane_b32 s62, v244, 49
	s_mul_hi_i32 s30, s28, 0xb0c000
	s_mul_i32 s40, s28, 0xb0c000
	v_readlane_b32 s63, v244, 50
	s_add_u32 s28, s62, s0
	v_readlane_b32 s46, v244, 9
	v_readlane_b32 s60, v244, 47
	s_addc_u32 s29, s63, s1
	v_readlane_b32 s47, v244, 10
	v_readlane_b32 s61, v244, 48
	s_add_u32 s46, s60, s0
	v_readlane_b32 s58, v244, 45
	s_addc_u32 s47, s61, s1
	s_lshl_b64 s[36:37], s[36:37], 2
	v_readlane_b32 s49, v244, 36
	v_readlane_b32 s59, v244, 46
	s_add_u32 s48, s58, s36
	v_readlane_b32 s50, v244, 37
	v_readlane_b32 s56, v244, 43
	s_addc_u32 s49, s59, s37
	v_readlane_b32 s51, v244, 38
	v_readlane_b32 s57, v244, 44
	s_add_u32 s50, s56, s38
	v_readlane_b32 s52, v244, 39
	s_addc_u32 s51, s57, s39
	v_readlane_b32 s53, v244, 40
	s_add_u32 s52, s52, s0
	v_readlane_b32 s42, v244, 5
	v_readlane_b32 s54, v244, 41
	s_addc_u32 s53, s53, s1
	v_readlane_b32 s43, v244, 6
	v_readlane_b32 s55, v244, 42
	s_add_u32 s54, s42, s36
	v_readlane_b32 s44, v244, 7
	s_addc_u32 s55, s43, s37
	v_readlane_b32 s45, v244, 8
	s_add_u32 s56, s44, s40
	s_addc_u32 s57, s45, s30
	s_branch .LBB0_782

; DEVI int vblk() { return (int)blockIdx.x * 2 + vhalf(); }
; DEVI int vgrid() { return (int)gridDim.x * 2; }
; DEVI void phase1(const Params& p, int l, char* lds) {
;     ...
;   for (int item = vblk(); item < n_items; item += vgrid()) {
;     int i = item;
;     if (i < P1_CVT) {
.LBB0_781:
	v_readlane_b32 s0, v244, 57
	v_readlane_b32 s1, v244, 58
	s_load_dword s0, s[0:1], 0x0
	s_waitcnt lgkmcnt(0)
	s_lshl_b32 s0, s0, 1
	s_add_i32 s23, s0, s23
	s_cmp_ge_i32 s23, s20
	s_cbranch_scc0 .Lp1_more
	s_cmp_eq_u32 s101, 0x5a5a
	s_cbranch_scc1 .Lcv_ret
	s_branch .LBB0_915
.Lp1_more:
.LBB0_782:
	s_cmp_eq_u32 s101, 0x5a5a
	s_cbranch_scc1 .Lp1_noskip
	s_cmpk_lt_i32 s23, 0x300
	s_cbranch_scc1 .Lp1_noskip
	s_cmpk_lt_i32 s23, 0x1100
	s_cbranch_scc1 .LBB0_781

; __global__ void __launch_bounds__(512, 2) fwd_mega(Params p, int ph_lo, int ph_hi, int coop) {
;     ...
;   for (int ph = ph_lo; ph < ph_hi; ++ph) {
;     run_phase(p, ph, lds, nsa_cnt_s, p4_stage, false);
;     ...
;     if ((REP_MASK >> (ph % PH_PER_LAYER)) & 1) { xcd_barrier(xb); run_phase(p, ph, lds, nsa_cnt_s, p4_stage, true); }
;     ...
;     for (int e = 0; e < EXTRA_SYNCS; ++e) xcd_barrier(xb);
;     ...
;     if (coop && ph + 1 < ph_hi) {
;       if (coop & 2) cg::this_grid().sync();
;       else xcd_barrier(xb);
;     }
.LBB0_915:
	s_add_i32 s92, s92, 1
	s_and_b32 s100, s92, 7
	s_lshr_b32 s101, s92, 3
	s_lshl_b32 s101, s101, 2
	s_cmp_eq_u32 s100, 0
	s_cbranch_scc1 .Llatch_set
	s_add_i32 s101, s101, 3
	s_cmp_eq_u32 s100, 6
	s_cselect_b32 s101, s101, 0

; __global__ void __launch_bounds__(512, 2) fwd_mega(Params p, int ph_lo, int ph_hi, int coop) {
;     ...
;     if (coop && ph + 1 < ph_hi) {
;       if (coop & 2) cg::this_grid().sync();
;       else xcd_barrier(xb);
;     }
.LBB0_962:
	s_mov_b32 s101, 0
	s_and_b32 s20, s92, 7
	s_cmp_eq_u32 s20, 1
	s_cbranch_scc1 .Lxb_global
	s_cmp_eq_u32 s20, 4
	s_cbranch_scc1 .Lxb_global
	v_readfirstlane_b32 s20, v246
	s_bcnt1_i32_b32 s20, s20
	s_cmp_lg_u32 s20, 1
	s_cbranch_scc1 .Lxb_global
	v_readfirstlane_b32 s20, v247
	s_bcnt1_i32_b32 s20, s20
	s_cmp_lg_u32 s20, 1
	s_cbranch_scc1 .Lxb_global
	v_readfirstlane_b32 s20, v248
	s_bcnt1_i32_b32 s20, s20
	s_cmp_lg_u32 s20, 1
	s_cbranch_scc1 .Lxb_global
	v_readfirstlane_b32 s20, v249
	s_bcnt1_i32_b32 s20, s20
	s_cmp_lg_u32 s20, 1
	s_cbranch_scc1 .Lxb_global
	v_readfirstlane_b32 s20, v250
	s_bcnt1_i32_b32 s20, s20
	s_cmp_lg_u32 s20, 1
	s_cbranch_scc1 .Lxb_global
	v_readfirstlane_b32 s20, v251
	s_bcnt1_i32_b32 s20, s20
	s_cmp_lg_u32 s20, 1
	s_cbranch_scc1 .Lxb_global
	v_readfirstlane_b32 s20, v252
	s_bcnt1_i32_b32 s20, s20
	s_cmp_lg_u32 s20, 1
	s_cbranch_scc1 .Lxb_global
	v_readfirstlane_b32 s20, v253
	s_bcnt1_i32_b32 s20, s20
	s_cmp_lg_u32 s20, 1
	s_cbranch_scc1 .Lxb_global
	s_and_b32 s20, s92, 7
	s_cmp_eq_u32 s20, 6
	s_cbranch_scc1 .Lxb_split
	s_cmp_eq_u32 s20, 0
	s_cbranch_scc0 .Lxb_local_leader
